# v27 + accumulator re-zeroing between GEMM units with 64-bit moves (63 v_mov_b64 + 1 v_mov_b32 instead of 127 v_mov_b32) in all six K-loops
# speedup vs baseline: 1.0157x; 1.0157x over previous
;     __device__ bool next(int i, Unit& u) const { const bool ok = StaticOrder::next(i / 3, u); u.seg = i % 3; return ok; }
; template <class Epi, class Sched>
; __device__ __forceinline__ void gemm_phase(LAS unsigned char* lds, const Gemm g, const Sched& S, const Epi& E) {
;     ...
;         const bool has_next = S.next(ui + 1, nxt);
;         const char* nA = has_next ? (const char*)g.A + (size_t)(g.fix ? 0 : nxt.pm) * tstepA + (size_t)S.koff(nxt) * 2 : cA; const char* nB = has_next ? (const char*)g.Bt + (size_t)(g.fix ? 0 : nxt.pn) * tstepB + (size_t)S.koff(nxt) * 2 : cB;
;         for (int t = 0; t < nt; t += 2) {
;             const bool last = (t == nt - 2);
;             const char* a1 = cA + (size_t)(t + 1) * kstep;
;             const char* a2 = last ? nA : cA + (size_t)(t + 2) * kstep; const char* b2 = last ? nB : cB + (size_t)(t + 2) * kstep;
;     ...
; #pragma unroll
;         for (int a = 0; a < 2; ++a)
; #pragma unroll
;             for (int b = 0; b < 2; ++b)
; #pragma unroll
;                 for (int m = 0; m < 4; ++m)
; #pragma unroll
;                     for (int n = 0; n < 2; ++n) acc[a][b][m][n] = (f32x4){0.f, 0.f, 0.f, 0.f};
;         cur = nxt; cA = nA; cB = nB; ++ui;
;         if (Sched::SEGMENTED) nt = S.nt(cur);
.LBB0_97:
	s_ashr_i32 s47, s46, 31
	s_lshl_b64 s[50:51], s[46:47], 20
	s_add_u32 s50, s72, s50
	s_addc_u32 s51, s73, s51
	s_and_b64 s[52:53], s[40:41], exec
	s_cselect_b32 s27, s51, s23
	s_cselect_b32 s47, s50, s22
	s_ashr_i32 s49, s48, 31
	s_lshl_b64 s[52:53], s[48:49], 20
	v_readlane_b32 s56, v252, 57
	v_readlane_b32 s57, v252, 58
	s_add_u32 s52, s56, s52
	s_addc_u32 s53, s57, s53
	s_and_b64 s[56:57], s[40:41], exec
	s_cselect_b32 s49, s53, s55
	s_cselect_b32 s61, s52, s54
	s_add_u32 s22, s22, 0x80080
	s_addc_u32 s23, s23, 0
	s_add_u32 s65, s54, 0x100
	v_mov_b32_e32 v0, 0
	s_addc_u32 s92, s55, 0
	s_mov_b32 s94, -2
	s_waitcnt lgkmcnt(0)
	v_mov_b32_e32 v1, 0
	v_mov_b64_e32 v[2:3], 0
	v_mov_b64_e32 v[4:5], 0
	v_mov_b64_e32 v[6:7], 0
	v_mov_b64_e32 v[8:9], 0
	v_mov_b64_e32 v[10:11], 0
	v_mov_b64_e32 v[12:13], 0
	v_mov_b64_e32 v[14:15], 0
	v_mov_b64_e32 v[16:17], 0
	v_mov_b64_e32 v[18:19], 0
	v_mov_b64_e32 v[20:21], 0
	v_mov_b64_e32 v[22:23], 0
	v_mov_b64_e32 v[24:25], 0
	v_mov_b64_e32 v[26:27], 0
	v_mov_b64_e32 v[28:29], 0
	v_mov_b64_e32 v[30:31], 0
	v_mov_b64_e32 v[32:33], 0
	v_mov_b64_e32 v[34:35], 0
	v_mov_b64_e32 v[36:37], 0
	v_mov_b64_e32 v[38:39], 0
	v_mov_b64_e32 v[40:41], 0
	v_mov_b64_e32 v[42:43], 0
	v_mov_b64_e32 v[44:45], 0
	v_mov_b64_e32 v[46:47], 0
	v_mov_b64_e32 v[48:49], 0
	v_mov_b64_e32 v[50:51], 0
	v_mov_b64_e32 v[52:53], 0
	v_mov_b64_e32 v[54:55], 0
	v_mov_b64_e32 v[56:57], 0
	v_mov_b64_e32 v[58:59], 0
	v_mov_b64_e32 v[60:61], 0
	v_mov_b64_e32 v[62:63], 0
	v_mov_b64_e32 v[64:65], 0
	v_mov_b64_e32 v[66:67], 0
	v_mov_b64_e32 v[68:69], 0
	v_mov_b64_e32 v[70:71], 0
	v_mov_b64_e32 v[72:73], 0
	v_mov_b64_e32 v[74:75], 0
	v_mov_b64_e32 v[76:77], 0
	v_mov_b64_e32 v[78:79], 0
	v_mov_b64_e32 v[80:81], 0
	v_mov_b64_e32 v[82:83], 0
	v_mov_b64_e32 v[84:85], 0
	v_mov_b64_e32 v[86:87], 0
	v_mov_b64_e32 v[88:89], 0
	v_mov_b64_e32 v[90:91], 0
	v_mov_b64_e32 v[92:93], 0
	v_mov_b64_e32 v[94:95], 0
	v_mov_b64_e32 v[96:97], 0
	v_mov_b64_e32 v[98:99], 0
	v_mov_b64_e32 v[100:101], 0
	v_mov_b64_e32 v[102:103], 0
	v_mov_b64_e32 v[104:105], 0
	v_mov_b64_e32 v[106:107], 0
	v_mov_b64_e32 v[108:109], 0
	v_mov_b64_e32 v[110:111], 0
	v_mov_b64_e32 v[112:113], 0
	v_mov_b64_e32 v[114:115], 0
	v_mov_b64_e32 v[116:117], 0
	v_mov_b64_e32 v[118:119], 0
	v_mov_b64_e32 v[120:121], 0
	v_mov_b64_e32 v[122:123], 0
	v_mov_b64_e32 v[124:125], 0
	v_mov_b64_e32 v[126:127], 0

;     __device__ bool next(int i, Unit& u) const { const bool ok = StaticOrder::next(i / 3, u); u.seg = i % 3; return ok; }
; template <class Epi, class Sched>
; __device__ __forceinline__ void gemm_phase(LAS unsigned char* lds, const Gemm g, const Sched& S, const Epi& E) {
;     ...
;         const bool has_next = S.next(ui + 1, nxt);
;         const char* nA = has_next ? (const char*)g.A + (size_t)(g.fix ? 0 : nxt.pm) * tstepA + (size_t)S.koff(nxt) * 2 : cA; const char* nB = has_next ? (const char*)g.Bt + (size_t)(g.fix ? 0 : nxt.pn) * tstepB + (size_t)S.koff(nxt) * 2 : cB;
;         for (int t = 0; t < nt; t += 2) {
;             const bool last = (t == nt - 2);
;             const char* a1 = cA + (size_t)(t + 1) * kstep;
;             const char* a2 = last ? nA : cA + (size_t)(t + 2) * kstep; const char* b2 = last ? nB : cB + (size_t)(t + 2) * kstep;
;     ...
; #pragma unroll
;         for (int a = 0; a < 2; ++a)
; #pragma unroll
;             for (int b = 0; b < 2; ++b)
; #pragma unroll
;                 for (int m = 0; m < 4; ++m)
; #pragma unroll
;                     for (int n = 0; n < 2; ++n) acc[a][b][m][n] = (f32x4){0.f, 0.f, 0.f, 0.f};
;         cur = nxt; cA = nA; cB = nB; ++ui;
;         if (Sched::SEGMENTED) nt = S.nt(cur);
.LBB0_140:
	s_add_i32 s20, s61, -2
	s_add_u32 s22, s22, 0x80080
	s_addc_u32 s23, s23, 0
	s_add_u32 s27, s40, 0x100
	v_mov_b32_e32 v0, 0
	s_addc_u32 s47, s41, 0
	s_mov_b32 s4, 0
	v_mov_b32_e32 v1, 0
	v_mov_b64_e32 v[2:3], 0
	v_mov_b64_e32 v[4:5], 0
	v_mov_b64_e32 v[6:7], 0
	v_mov_b64_e32 v[8:9], 0
	v_mov_b64_e32 v[10:11], 0
	v_mov_b64_e32 v[12:13], 0
	v_mov_b64_e32 v[14:15], 0
	v_mov_b64_e32 v[16:17], 0
	v_mov_b64_e32 v[18:19], 0
	v_mov_b64_e32 v[20:21], 0
	v_mov_b64_e32 v[22:23], 0
	v_mov_b64_e32 v[24:25], 0
	v_mov_b64_e32 v[26:27], 0
	v_mov_b64_e32 v[28:29], 0
	v_mov_b64_e32 v[30:31], 0
	v_mov_b64_e32 v[32:33], 0
	v_mov_b64_e32 v[34:35], 0
	v_mov_b64_e32 v[36:37], 0
	v_mov_b64_e32 v[38:39], 0
	v_mov_b64_e32 v[40:41], 0
	v_mov_b64_e32 v[42:43], 0
	v_mov_b64_e32 v[44:45], 0
	v_mov_b64_e32 v[46:47], 0
	v_mov_b64_e32 v[48:49], 0
	v_mov_b64_e32 v[50:51], 0
	v_mov_b64_e32 v[52:53], 0
	v_mov_b64_e32 v[54:55], 0
	v_mov_b64_e32 v[56:57], 0
	v_mov_b64_e32 v[58:59], 0
	v_mov_b64_e32 v[60:61], 0
	v_mov_b64_e32 v[62:63], 0
	v_mov_b64_e32 v[64:65], 0
	v_mov_b64_e32 v[66:67], 0
	v_mov_b64_e32 v[68:69], 0
	v_mov_b64_e32 v[70:71], 0
	v_mov_b64_e32 v[72:73], 0
	v_mov_b64_e32 v[74:75], 0
	v_mov_b64_e32 v[76:77], 0
	v_mov_b64_e32 v[78:79], 0
	v_mov_b64_e32 v[80:81], 0
	v_mov_b64_e32 v[82:83], 0
	v_mov_b64_e32 v[84:85], 0
	v_mov_b64_e32 v[86:87], 0
	v_mov_b64_e32 v[88:89], 0
	v_mov_b64_e32 v[90:91], 0
	v_mov_b64_e32 v[92:93], 0
	v_mov_b64_e32 v[94:95], 0
	v_mov_b64_e32 v[96:97], 0
	v_mov_b64_e32 v[98:99], 0
	v_mov_b64_e32 v[100:101], 0
	v_mov_b64_e32 v[102:103], 0
	v_mov_b64_e32 v[104:105], 0
	v_mov_b64_e32 v[106:107], 0
	v_mov_b64_e32 v[108:109], 0
	v_mov_b64_e32 v[110:111], 0
	v_mov_b64_e32 v[112:113], 0
	v_mov_b64_e32 v[114:115], 0
	v_mov_b64_e32 v[116:117], 0
	v_mov_b64_e32 v[118:119], 0
	v_mov_b64_e32 v[120:121], 0
	v_mov_b64_e32 v[122:123], 0
	v_mov_b64_e32 v[124:125], 0
	v_mov_b64_e32 v[126:127], 0

;     __device__ bool next(int i, Unit& u) const { const bool ok = StaticOrder::next(i / 3, u); u.seg = i % 3; return ok; }
; template <class Epi, class Sched>
; __device__ __forceinline__ void gemm_phase(LAS unsigned char* lds, const Gemm g, const Sched& S, const Epi& E) {
;     ...
;         const bool has_next = S.next(ui + 1, nxt);
;         const char* nA = has_next ? (const char*)g.A + (size_t)(g.fix ? 0 : nxt.pm) * tstepA + (size_t)S.koff(nxt) * 2 : cA; const char* nB = has_next ? (const char*)g.Bt + (size_t)(g.fix ? 0 : nxt.pn) * tstepB + (size_t)S.koff(nxt) * 2 : cB;
;         for (int t = 0; t < nt; t += 2) {
;             const bool last = (t == nt - 2);
;             const char* a1 = cA + (size_t)(t + 1) * kstep;
;             const char* a2 = last ? nA : cA + (size_t)(t + 2) * kstep; const char* b2 = last ? nB : cB + (size_t)(t + 2) * kstep;
;     ...
; #pragma unroll
;         for (int a = 0; a < 2; ++a)
; #pragma unroll
;             for (int b = 0; b < 2; ++b)
; #pragma unroll
;                 for (int m = 0; m < 4; ++m)
; #pragma unroll
;                     for (int n = 0; n < 2; ++n) acc[a][b][m][n] = (f32x4){0.f, 0.f, 0.f, 0.f};
;         cur = nxt; cA = nA; cB = nB; ++ui;
;         if (Sched::SEGMENTED) nt = S.nt(cur);
.LBB0_196:
	s_ashr_i32 s41, s40, 31
	s_lshl_b64 s[44:45], s[40:41], 18
	s_add_u32 s44, s74, s44
	s_addc_u32 s45, s75, s45
	s_and_b64 s[46:47], s[38:39], exec
	s_cselect_b32 s27, s45, s49
	s_cselect_b32 s41, s44, s48
	s_ashr_i32 s43, s42, 31
	s_lshl_b64 s[46:47], s[42:43], 18
	v_readlane_b32 s52, v252, 35
	v_readlane_b32 s53, v252, 36
	s_add_u32 s46, s52, s46
	s_addc_u32 s47, s53, s47
	s_and_b64 s[52:53], s[38:39], exec
	s_cselect_b32 s43, s47, s51
	s_cselect_b32 s60, s46, s50
	s_add_u32 s48, s48, 0x20080
	s_addc_u32 s49, s49, 0
	s_add_u32 s61, s50, 0x100
	v_mov_b32_e32 v0, 0
	s_addc_u32 s62, s51, 0
	s_mov_b32 s63, -2
	v_mov_b32_e32 v1, 0
	v_mov_b64_e32 v[2:3], 0
	v_mov_b64_e32 v[4:5], 0
	v_mov_b64_e32 v[6:7], 0
	v_mov_b64_e32 v[8:9], 0
	v_mov_b64_e32 v[10:11], 0
	v_mov_b64_e32 v[12:13], 0
	v_mov_b64_e32 v[14:15], 0
	v_mov_b64_e32 v[16:17], 0
	v_mov_b64_e32 v[18:19], 0
	v_mov_b64_e32 v[20:21], 0
	v_mov_b64_e32 v[22:23], 0
	v_mov_b64_e32 v[24:25], 0
	v_mov_b64_e32 v[26:27], 0
	v_mov_b64_e32 v[28:29], 0
	v_mov_b64_e32 v[30:31], 0
	v_mov_b64_e32 v[32:33], 0
	v_mov_b64_e32 v[34:35], 0
	v_mov_b64_e32 v[36:37], 0
	v_mov_b64_e32 v[38:39], 0
	v_mov_b64_e32 v[40:41], 0
	v_mov_b64_e32 v[42:43], 0
	v_mov_b64_e32 v[44:45], 0
	v_mov_b64_e32 v[46:47], 0
	v_mov_b64_e32 v[48:49], 0
	v_mov_b64_e32 v[50:51], 0
	v_mov_b64_e32 v[52:53], 0
	v_mov_b64_e32 v[54:55], 0
	v_mov_b64_e32 v[56:57], 0
	v_mov_b64_e32 v[58:59], 0
	v_mov_b64_e32 v[60:61], 0
	v_mov_b64_e32 v[62:63], 0
	v_mov_b64_e32 v[64:65], 0
	v_mov_b64_e32 v[66:67], 0
	v_mov_b64_e32 v[68:69], 0
	v_mov_b64_e32 v[70:71], 0
	v_mov_b64_e32 v[72:73], 0
	v_mov_b64_e32 v[74:75], 0
	v_mov_b64_e32 v[76:77], 0
	v_mov_b64_e32 v[78:79], 0
	v_mov_b64_e32 v[80:81], 0
	v_mov_b64_e32 v[82:83], 0
	v_mov_b64_e32 v[84:85], 0
	v_mov_b64_e32 v[86:87], 0
	v_mov_b64_e32 v[88:89], 0
	v_mov_b64_e32 v[90:91], 0
	v_mov_b64_e32 v[92:93], 0
	v_mov_b64_e32 v[94:95], 0
	v_mov_b64_e32 v[96:97], 0
	v_mov_b64_e32 v[98:99], 0
	v_mov_b64_e32 v[100:101], 0
	v_mov_b64_e32 v[102:103], 0
	v_mov_b64_e32 v[104:105], 0
	v_mov_b64_e32 v[106:107], 0
	v_mov_b64_e32 v[108:109], 0
	v_mov_b64_e32 v[110:111], 0
	v_mov_b64_e32 v[112:113], 0
	v_mov_b64_e32 v[114:115], 0
	v_mov_b64_e32 v[116:117], 0
	v_mov_b64_e32 v[118:119], 0
	v_mov_b64_e32 v[120:121], 0
	v_mov_b64_e32 v[122:123], 0
	v_mov_b64_e32 v[124:125], 0
	v_mov_b64_e32 v[126:127], 0

;     __device__ bool next(int i, Unit& u) const { const bool ok = StaticOrder::next(i / 3, u); u.seg = i % 3; return ok; }
; template <class Epi, class Sched>
; __device__ __forceinline__ void gemm_phase(LAS unsigned char* lds, const Gemm g, const Sched& S, const Epi& E) {
;     ...
;         const bool has_next = S.next(ui + 1, nxt);
;         const char* nA = has_next ? (const char*)g.A + (size_t)(g.fix ? 0 : nxt.pm) * tstepA + (size_t)S.koff(nxt) * 2 : cA; const char* nB = has_next ? (const char*)g.Bt + (size_t)(g.fix ? 0 : nxt.pn) * tstepB + (size_t)S.koff(nxt) * 2 : cB;
;         for (int t = 0; t < nt; t += 2) {
;             const bool last = (t == nt - 2);
;             const char* a1 = cA + (size_t)(t + 1) * kstep;
;             const char* a2 = last ? nA : cA + (size_t)(t + 2) * kstep; const char* b2 = last ? nB : cB + (size_t)(t + 2) * kstep;
;     ...
; #pragma unroll
;         for (int a = 0; a < 2; ++a)
; #pragma unroll
;             for (int b = 0; b < 2; ++b)
; #pragma unroll
;                 for (int m = 0; m < 4; ++m)
; #pragma unroll
;                     for (int n = 0; n < 2; ++n) acc[a][b][m][n] = (f32x4){0.f, 0.f, 0.f, 0.f};
;         cur = nxt; cA = nA; cB = nB; ++ui;
;         if (Sched::SEGMENTED) nt = S.nt(cur);
.LBB0_381:
	s_ashr_i32 s49, s48, 31
	s_lshl_b64 s[40:41], s[48:49], 20
	s_add_u32 s52, s90, s40
	s_addc_u32 s53, s91, s41
	s_and_b64 s[40:41], s[38:39], exec
	s_cselect_b32 s20, s53, s1
	s_cselect_b32 s27, s52, s0
	s_ashr_i32 s51, s50, 31
	s_lshl_b64 s[40:41], s[50:51], 20
	v_readlane_b32 s54, v253, 19
	v_readlane_b32 s55, v253, 20
	s_add_u32 s54, s54, s40
	s_addc_u32 s55, s55, s41
	s_and_b64 s[40:41], s[38:39], exec
	s_cselect_b32 s49, s55, s23
	s_cselect_b32 s51, s54, s22
	s_add_u32 s0, s0, 0x80080
	s_addc_u32 s1, s1, 0
	s_add_u32 s63, s22, 0x100
	v_mov_b32_e32 v0, 0
	s_addc_u32 s64, s23, 0
	s_mov_b32 s65, -2
	v_mov_b32_e32 v1, 0
	v_mov_b64_e32 v[2:3], 0
	v_mov_b64_e32 v[4:5], 0
	v_mov_b64_e32 v[6:7], 0
	v_mov_b64_e32 v[8:9], 0
	v_mov_b64_e32 v[10:11], 0
	v_mov_b64_e32 v[12:13], 0
	v_mov_b64_e32 v[14:15], 0
	v_mov_b64_e32 v[16:17], 0
	v_mov_b64_e32 v[18:19], 0
	v_mov_b64_e32 v[20:21], 0
	v_mov_b64_e32 v[22:23], 0
	v_mov_b64_e32 v[24:25], 0
	v_mov_b64_e32 v[26:27], 0
	v_mov_b64_e32 v[28:29], 0
	v_mov_b64_e32 v[30:31], 0
	v_mov_b64_e32 v[32:33], 0
	v_mov_b64_e32 v[34:35], 0
	v_mov_b64_e32 v[36:37], 0
	v_mov_b64_e32 v[38:39], 0
	v_mov_b64_e32 v[40:41], 0
	v_mov_b64_e32 v[42:43], 0
	v_mov_b64_e32 v[44:45], 0
	v_mov_b64_e32 v[46:47], 0
	v_mov_b64_e32 v[48:49], 0
	v_mov_b64_e32 v[50:51], 0
	v_mov_b64_e32 v[52:53], 0
	v_mov_b64_e32 v[54:55], 0
	v_mov_b64_e32 v[56:57], 0
	v_mov_b64_e32 v[58:59], 0
	v_mov_b64_e32 v[60:61], 0
	v_mov_b64_e32 v[62:63], 0
	v_mov_b64_e32 v[64:65], 0
	v_mov_b64_e32 v[66:67], 0
	v_mov_b64_e32 v[68:69], 0
	v_mov_b64_e32 v[70:71], 0
	v_mov_b64_e32 v[72:73], 0
	v_mov_b64_e32 v[74:75], 0
	v_mov_b64_e32 v[76:77], 0
	v_mov_b64_e32 v[78:79], 0
	v_mov_b64_e32 v[80:81], 0
	v_mov_b64_e32 v[82:83], 0
	v_mov_b64_e32 v[84:85], 0
	v_mov_b64_e32 v[86:87], 0
	v_mov_b64_e32 v[88:89], 0
	v_mov_b64_e32 v[90:91], 0
	v_mov_b64_e32 v[92:93], 0
	v_mov_b64_e32 v[94:95], 0
	v_mov_b64_e32 v[96:97], 0
	v_mov_b64_e32 v[98:99], 0
	v_mov_b64_e32 v[100:101], 0
	v_mov_b64_e32 v[102:103], 0
	v_mov_b64_e32 v[104:105], 0
	v_mov_b64_e32 v[106:107], 0
	v_mov_b64_e32 v[108:109], 0
	v_mov_b64_e32 v[110:111], 0
	v_mov_b64_e32 v[112:113], 0
	v_mov_b64_e32 v[114:115], 0
	v_mov_b64_e32 v[116:117], 0
	v_mov_b64_e32 v[118:119], 0
	v_mov_b64_e32 v[120:121], 0
	v_mov_b64_e32 v[122:123], 0
	v_mov_b64_e32 v[124:125], 0
	v_mov_b64_e32 v[126:127], 0

;     __device__ bool next(int i, Unit& u) const { const bool ok = StaticOrder::next(i / 3, u); u.seg = i % 3; return ok; }
; template <class Epi, class Sched>
; __device__ __forceinline__ void gemm_phase(LAS unsigned char* lds, const Gemm g, const Sched& S, const Epi& E) {
;     ...
;         const bool has_next = S.next(ui + 1, nxt);
;         const char* nA = has_next ? (const char*)g.A + (size_t)(g.fix ? 0 : nxt.pm) * tstepA + (size_t)S.koff(nxt) * 2 : cA; const char* nB = has_next ? (const char*)g.Bt + (size_t)(g.fix ? 0 : nxt.pn) * tstepB + (size_t)S.koff(nxt) * 2 : cB;
;         for (int t = 0; t < nt; t += 2) {
;             const bool last = (t == nt - 2);
;             const char* a1 = cA + (size_t)(t + 1) * kstep;
;             const char* a2 = last ? nA : cA + (size_t)(t + 2) * kstep; const char* b2 = last ? nB : cB + (size_t)(t + 2) * kstep;
;     ...
; #pragma unroll
;         for (int a = 0; a < 2; ++a)
; #pragma unroll
;             for (int b = 0; b < 2; ++b)
; #pragma unroll
;                 for (int m = 0; m < 4; ++m)
; #pragma unroll
;                     for (int n = 0; n < 2; ++n) acc[a][b][m][n] = (f32x4){0.f, 0.f, 0.f, 0.f};
;         cur = nxt; cA = nA; cB = nB; ++ui;
;         if (Sched::SEGMENTED) nt = S.nt(cur);
.LBB0_678:
	s_add_u32 vcc_lo, s54, 0x100
	v_mov_b32_e32 v0, 0
	s_addc_u32 vcc_hi, s55, 0
	s_mov_b32 s4, -2
	s_waitcnt lgkmcnt(0)
	v_mov_b32_e32 v1, 0
	v_mov_b64_e32 v[2:3], 0
	v_mov_b64_e32 v[4:5], 0
	v_mov_b64_e32 v[6:7], 0
	v_mov_b64_e32 v[8:9], 0
	v_mov_b64_e32 v[10:11], 0
	v_mov_b64_e32 v[12:13], 0
	v_mov_b64_e32 v[14:15], 0
	v_mov_b64_e32 v[16:17], 0
	v_mov_b64_e32 v[18:19], 0
	v_mov_b64_e32 v[20:21], 0
	v_mov_b64_e32 v[22:23], 0
	v_mov_b64_e32 v[24:25], 0
	v_mov_b64_e32 v[26:27], 0
	v_mov_b64_e32 v[28:29], 0
	v_mov_b64_e32 v[30:31], 0
	v_mov_b64_e32 v[32:33], 0
	v_mov_b64_e32 v[34:35], 0
	v_mov_b64_e32 v[36:37], 0
	v_mov_b64_e32 v[38:39], 0
	v_mov_b64_e32 v[40:41], 0
	v_mov_b64_e32 v[42:43], 0
	v_mov_b64_e32 v[44:45], 0
	v_mov_b64_e32 v[46:47], 0
	v_mov_b64_e32 v[48:49], 0
	v_mov_b64_e32 v[50:51], 0
	v_mov_b64_e32 v[52:53], 0
	v_mov_b64_e32 v[54:55], 0
	v_mov_b64_e32 v[56:57], 0
	v_mov_b64_e32 v[58:59], 0
	v_mov_b64_e32 v[60:61], 0
	v_mov_b64_e32 v[62:63], 0
	v_mov_b64_e32 v[64:65], 0
	v_mov_b64_e32 v[66:67], 0
	v_mov_b64_e32 v[68:69], 0
	v_mov_b64_e32 v[70:71], 0
	v_mov_b64_e32 v[72:73], 0
	v_mov_b64_e32 v[74:75], 0
	v_mov_b64_e32 v[76:77], 0
	v_mov_b64_e32 v[78:79], 0
	v_mov_b64_e32 v[80:81], 0
	v_mov_b64_e32 v[82:83], 0
	v_mov_b64_e32 v[84:85], 0
	v_mov_b64_e32 v[86:87], 0
	v_mov_b64_e32 v[88:89], 0
	v_mov_b64_e32 v[90:91], 0
	v_mov_b64_e32 v[92:93], 0
	v_mov_b64_e32 v[94:95], 0
	v_mov_b64_e32 v[96:97], 0
	v_mov_b64_e32 v[98:99], 0
	v_mov_b64_e32 v[100:101], 0
	v_mov_b64_e32 v[102:103], 0
	v_mov_b64_e32 v[104:105], 0
	v_mov_b64_e32 v[106:107], 0
	v_mov_b64_e32 v[108:109], 0
	v_mov_b64_e32 v[110:111], 0
	v_mov_b64_e32 v[112:113], 0
	v_mov_b64_e32 v[114:115], 0
	v_mov_b64_e32 v[116:117], 0
	v_mov_b64_e32 v[118:119], 0
	v_mov_b64_e32 v[120:121], 0
	v_mov_b64_e32 v[122:123], 0
	v_mov_b64_e32 v[124:125], 0
	v_mov_b64_e32 v[126:127], 0

;     __device__ bool next(int i, Unit& u) const { const bool ok = StaticOrder::next(i / 3, u); u.seg = i % 3; return ok; }
; template <class Epi, class Sched>
; __device__ __forceinline__ void gemm_phase(LAS unsigned char* lds, const Gemm g, const Sched& S, const Epi& E) {
;     ...
;         const bool has_next = S.next(ui + 1, nxt);
;         const char* nA = has_next ? (const char*)g.A + (size_t)(g.fix ? 0 : nxt.pm) * tstepA + (size_t)S.koff(nxt) * 2 : cA; const char* nB = has_next ? (const char*)g.Bt + (size_t)(g.fix ? 0 : nxt.pn) * tstepB + (size_t)S.koff(nxt) * 2 : cB;
;         for (int t = 0; t < nt; t += 2) {
;             const bool last = (t == nt - 2);
;             const char* a1 = cA + (size_t)(t + 1) * kstep;
;             const char* a2 = last ? nA : cA + (size_t)(t + 2) * kstep; const char* b2 = last ? nB : cB + (size_t)(t + 2) * kstep;
;     ...
; #pragma unroll
;         for (int a = 0; a < 2; ++a)
; #pragma unroll
;             for (int b = 0; b < 2; ++b)
; #pragma unroll
;                 for (int m = 0; m < 4; ++m)
; #pragma unroll
;                     for (int n = 0; n < 2; ++n) acc[a][b][m][n] = (f32x4){0.f, 0.f, 0.f, 0.f};
;         cur = nxt; cA = nA; cB = nB; ++ui;
;         if (Sched::SEGMENTED) nt = S.nt(cur);
.LBB0_744:
	s_ashr_i32 s45, s44, 31
	s_lshl_b64 s[48:49], s[44:45], 20
	s_add_u32 s48, s90, s48
	s_addc_u32 s49, s91, s49
	s_and_b64 s[50:51], s[38:39], exec
	s_cselect_b32 s45, s49, s23
	s_cselect_b32 s60, s48, s22
	s_ashr_i32 s47, s46, 31
	s_lshl_b64 s[50:51], s[46:47], 20
	s_add_u32 s50, s28, s50
	s_addc_u32 s51, s30, s51
	s_and_b64 s[54:55], s[38:39], exec
	s_cselect_b32 s47, s51, s53
	s_cselect_b32 s61, s50, s52
	s_add_u32 s22, s22, 0x80080
	s_addc_u32 s23, s23, 0
	s_add_u32 s65, s52, 0x100
	v_mov_b32_e32 v0, 0
	s_addc_u32 s92, s53, 0
	s_mov_b32 s94, -2
	v_mov_b32_e32 v1, 0
	v_mov_b64_e32 v[2:3], 0
	v_mov_b64_e32 v[4:5], 0
	v_mov_b64_e32 v[6:7], 0
	v_mov_b64_e32 v[8:9], 0
	v_mov_b64_e32 v[10:11], 0
	v_mov_b64_e32 v[12:13], 0
	v_mov_b64_e32 v[14:15], 0
	v_mov_b64_e32 v[16:17], 0
	v_mov_b64_e32 v[18:19], 0
	v_mov_b64_e32 v[20:21], 0
	v_mov_b64_e32 v[22:23], 0
	v_mov_b64_e32 v[24:25], 0
	v_mov_b64_e32 v[26:27], 0
	v_mov_b64_e32 v[28:29], 0
	v_mov_b64_e32 v[30:31], 0
	v_mov_b64_e32 v[32:33], 0
	v_mov_b64_e32 v[34:35], 0
	v_mov_b64_e32 v[36:37], 0
	v_mov_b64_e32 v[38:39], 0
	v_mov_b64_e32 v[40:41], 0
	v_mov_b64_e32 v[42:43], 0
	v_mov_b64_e32 v[44:45], 0
	v_mov_b64_e32 v[46:47], 0
	v_mov_b64_e32 v[48:49], 0
	v_mov_b64_e32 v[50:51], 0
	v_mov_b64_e32 v[52:53], 0
	v_mov_b64_e32 v[54:55], 0
	v_mov_b64_e32 v[56:57], 0
	v_mov_b64_e32 v[58:59], 0
	v_mov_b64_e32 v[60:61], 0
	v_mov_b64_e32 v[62:63], 0
	v_mov_b64_e32 v[64:65], 0
	v_mov_b64_e32 v[66:67], 0
	v_mov_b64_e32 v[68:69], 0
	v_mov_b64_e32 v[70:71], 0
	v_mov_b64_e32 v[72:73], 0
	v_mov_b64_e32 v[74:75], 0
	v_mov_b64_e32 v[76:77], 0
	v_mov_b64_e32 v[78:79], 0
	v_mov_b64_e32 v[80:81], 0
	v_mov_b64_e32 v[82:83], 0
	v_mov_b64_e32 v[84:85], 0
	v_mov_b64_e32 v[86:87], 0
	v_mov_b64_e32 v[88:89], 0
	v_mov_b64_e32 v[90:91], 0
	v_mov_b64_e32 v[92:93], 0
	v_mov_b64_e32 v[94:95], 0
	v_mov_b64_e32 v[96:97], 0
	v_mov_b64_e32 v[98:99], 0
	v_mov_b64_e32 v[100:101], 0
	v_mov_b64_e32 v[102:103], 0
	v_mov_b64_e32 v[104:105], 0
	v_mov_b64_e32 v[106:107], 0
	v_mov_b64_e32 v[108:109], 0
	v_mov_b64_e32 v[110:111], 0
	v_mov_b64_e32 v[112:113], 0
	v_mov_b64_e32 v[114:115], 0
	v_mov_b64_e32 v[116:117], 0
	v_mov_b64_e32 v[118:119], 0
	v_mov_b64_e32 v[120:121], 0
	v_mov_b64_e32 v[122:123], 0
	v_mov_b64_e32 v[124:125], 0
	v_mov_b64_e32 v[126:127], 0
